# grid barrier: non-leader workgroups poll the top-level generation word directly instead of waiting for the per-XCD release hop
# speedup vs baseline: 1.0608x; 1.0020x over previous
.LBB0_2037:
	s_or_b64 exec, exec, s[12:13]
	s_waitcnt vmcnt(0)
	v_readfirstlane_b32 s0, v3
	v_sub_u32_e32 v4, 0, v2
	s_nop 0
	v_add_u32_e32 v3, s0, v1
	v_cvt_f32_u32_e32 v1, v2
	v_rcp_iflag_f32_e32 v1, v1
	s_nop 0
	v_mul_f32_e32 v1, 0x4f7ffffe, v1
	v_cvt_u32_f32_e32 v1, v1
	v_mul_lo_u32 v4, v4, v1
	v_mul_hi_u32 v4, v1, v4
	v_add_u32_e32 v1, v1, v4
	v_mul_hi_u32 v1, v3, v1
	v_mul_lo_u32 v4, v1, v2
	v_sub_u32_e32 v4, v3, v4
	v_cmp_ge_u32_e32 vcc, v4, v2
	v_add_u32_e32 v5, 1, v1
	s_nop 0
	v_cndmask_b32_e32 v1, v1, v5, vcc
	v_sub_u32_e32 v5, v4, v2
	v_cndmask_b32_e32 v4, v4, v5, vcc
	v_cmp_ge_u32_e32 vcc, v4, v2
	v_add_u32_e32 v4, 1, v1
	s_nop 0
	v_cndmask_b32_e32 v1, v1, v4, vcc
	v_add_u32_e32 v4, 1, v3
	v_mad_u64_u32 v[2:3], s[0:1], v2, v1, v[2:3]
	v_cmp_ne_u32_e32 vcc, v4, v2
	s_and_saveexec_b64 s[0:1], vcc
	s_xor_b64 s[10:11], exec, s[0:1]
	s_cbranch_execz .LBB0_2051
	v_mov_b32_e32 v0, 0x3500
	global_load_dword v0, v0, s[2:3] sc1
	s_add_u32 s14, s2, 0x3500
	s_addc_u32 s15, s3, 0
	s_waitcnt vmcnt(0)
	v_cmp_eq_u32_e32 vcc, v0, v1
	s_and_saveexec_b64 s[12:13], vcc
	s_cbranch_execz .LBB0_2050
	s_mov_b32 s0, 1
	s_mov_b64 s[16:17], 0
	s_branch .LBB0_2041
